# step-4 LN stats loads issued together + retention vmcnt ladder counted past stores
# speedup vs baseline: 1.0001x; 1.0001x over previous
; #define LAS __attribute__((address_space(3)))
; __device__ __forceinline__ void ret_item(LAS unsigned char* lds, const bf16_t* proj, bf16_t* OD, int b, int h, int dir, int vs, float lg2) {
;     ...
;     const float c16 = __builtin_amdgcn_exp2f(16.f * lg2), c32 = c16 * c16, c48 = c32 * c16, cd = c32 * c32;
;     const float qdl = __builtin_amdgcn_exp2f((float)(dir ? 16 - l15 : l15 + 1) * lg2);
;     float kd8[8], d4[4];
; #pragma unroll
;     for (int r = 0; r < 4; ++r) d4[r] = __builtin_amdgcn_exp2f((float)(dir ? 4 * g + r - l15 : l15 - 4 * g - r) * lg2);
; #pragma unroll
;     for (int jj = 0; jj < 8; ++jj) kd8[jj] = __builtin_amdgcn_exp2f((float)(dir ? 8 * g + jj : 31 - 8 * g - jj) * lg2);
;     const int b3 = (l15 >> 3) & 1, sit = wid >> 1, sjt0 = 2 * (wid & 1), lo2 = 32 * (g & 1) + 8 * (g >> 1);
;     LAS unsigned char* pSk = lds + KS + (16 * sjt0 + l15) * RSQ + ((16 * g) ^ (32 * b3));
;     LAS unsigned char* pSq = lds + QS + (16 * sit + l15) * RSQ + (lo2 ^ (32 * b3));
;     LAS unsigned char* pCq = lds + QS + l15 * RSQ + ((16 * g) ^ (32 * b3));
;     LAS unsigned char* pIs = lds + SP + l15 * RSS + 16 * g;
;     LAS unsigned char* pVt = lds + VS + (8 * g + q4) * RSV + (16 * wid + 4 * pp) * 2;
;     LAS unsigned char* pKe = lds + KS + (8 * g + q4) * RSQ + 8 * pp + 32 * (g & 1);
;     LAS unsigned char* pKo = lds + KS + (8 * g + q4) * RSQ + 8 * pp - 32 * (g & 1);
;     const int sb3 = (qrow >> 3) & 1;
;     LAS unsigned char* wQ = lds + QS + qrow * RSQ + ((16 * qpc) ^ (32 * sb3));
;     LAS unsigned char* wK0 = lds + KS + qrow * RSQ + ((64 * (qpc >> 2) + 8 * (qpc & 3)) ^ (32 * sb3));
;     LAS unsigned char* wK1 = lds + KS + qrow * RSQ + ((64 * (qpc >> 2) + 32 + 8 * (qpc & 3)) ^ (32 * sb3));
; __global__ void __launch_bounds__(512, 2) mega_fwd(Params p) {
;     ...
;                 const int xcd = u & 7, slot = u >> 3, bh = xcd * 4 + (slot >> 3), sub = slot & 7, dir = sub >> 2, vs = sub & 3, b = bh >> 3, h = bh & 7;
;                 const float e = p.r_dec[j * 16 + dir * 8 + h]; const float xg = __builtin_amdgcn_exp2f(-e);
;                 const float lg = -(xg * (1.f + xg * (0.5f + xg * (1.f / 3 + xg * (0.25f + xg * (0.2f + xg * (1.f / 6)))))));
;                 ret::ret_item(lds, proj, dir ? OB : OF, b, h, dir, vs, lg * 1.4426950408889634f);
.LBB0_139:
	s_lshl_b32 s16, s15, 2
	s_and_b32 s16, s16, 28
	s_ashr_i32 s17, s15, 6
	s_bfe_u32 s21, s15, 0x10005
	s_add_i32 s24, s16, s17
	s_lshl_b32 s16, s21, 3
	s_and_b32 s26, s24, 7
	s_or_b32 s16, s16, s14
	s_or_b32 s72, s16, s26
	v_readlane_b32 s36, v253, 0
	s_lshl_b64 s[16:17], s[72:73], 2
	v_readlane_b32 s48, v253, 12
	v_readlane_b32 s49, v253, 13
	s_add_u32 s16, s48, s16
	s_addc_u32 s17, s49, s17
	global_load_dword v0, v177, s[16:17]
	s_waitcnt vmcnt(14)
	v_mov_b32_e32 v1, v252
	v_readlane_b32 s37, v253, 1
	v_readfirstlane_b32 s17, v1
	s_ashr_i32 s20, s17, 6
	s_ashr_i32 s25, s17, 7
	s_lshl_b32 s17, s20, 1
	s_and_b32 s17, s17, 2
	s_or_b32 s18, s17, 1
	s_sub_i32 s27, s17, s25
	s_sub_i32 s19, s18, s25
	s_sub_i32 s28, s25, s18
	s_cmp_eq_u32 s21, 0
	s_cselect_b64 s[22:23], -1, 0
	v_bfe_u32 v2, v1, 4, 2
	s_and_b64 s[22:23], s[22:23], exec
	v_lshlrev_b32_e32 v41, 2, v2
	s_cselect_b32 s19, s28, s19
	s_sub_i32 s28, s25, s17
	v_and_b32_e32 v40, 15, v1
	s_waitcnt vmcnt(13)
	v_or_b32_e32 v7, 1, v41
	s_cmp_eq_u32 s21, 0
	v_sub_u32_e32 v3, 16, v40
	v_add_u32_e32 v4, 1, v40
	v_sub_co_u32_e32 v5, vcc, v41, v40
	v_sub_u32_e32 v6, v40, v41
	s_waitcnt vmcnt(12)
	v_sub_u32_e32 v8, v7, v40
	v_sub_u32_e32 v7, v40, v7
	s_cselect_b64 s[36:37], -1, 0
	v_cndmask_b32_e64 v3, v3, v4, s[36:37]
	v_cndmask_b32_e64 v4, v5, v6, s[36:37]
	v_cndmask_b32_e64 v5, v8, v7, s[36:37]
	v_mov_b32_e32 v7, 0x3e4ccccd
	v_or_b32_e32 v43, 2, v41
	v_sub_u32_e32 v9, v43, v40
	v_sub_u32_e32 v10, v40, v43
	v_cndmask_b32_e64 v6, v9, v10, s[36:37]
	v_cvt_f32_i32_e32 v4, v4
	v_cvt_f32_i32_e32 v5, v5
	v_cvt_f32_i32_e32 v6, v6
	v_cvt_f32_ubyte0_e32 v3, v3
	v_lshlrev_b32_e32 v176, 3, v2
	v_readlane_b32 s41, v253, 5
	s_and_b64 s[22:23], s[36:37], exec
	s_cselect_b32 s29, s7, s9
	s_cselect_b32 s41, s6, s8
	s_cselect_b32 s21, s28, s27
	s_lshl_b32 s22, s24, 9
	v_readlane_b32 s40, v253, 4
	s_and_b32 s22, s22, 0xfffff000
	s_bfe_i32 s40, s15, 0x10005
	s_ashr_i32 s23, s22, 31
	s_mul_i32 s27, s22, 0x6000
	s_mul_hi_i32 s24, s22, 0x6000
	s_add_u32 s28, s4, s27
	v_readlane_b32 s38, v253, 2
	s_addc_u32 s24, s5, s24
	s_lshl_b32 s27, s26, 9
	v_readlane_b32 s39, v253, 3
	s_add_u32 s38, s28, s27
	v_or_b32_e32 v42, 3, v41
	s_addc_u32 s39, s24, 0
	s_lshl_b64 s[22:23], s[22:23], 13
	v_sub_u32_e32 v11, v42, v40
	s_add_u32 s22, s41, s22
	s_addc_u32 s23, s29, s23
	s_lshl_b32 s29, s26, 10
	v_readlane_b32 s42, v253, 6
	s_add_u32 s41, s22, s29
	s_addc_u32 s42, s23, 0
	s_lshl_b32 s26, s20, 4
	s_ashr_i32 s27, s26, 31
	s_add_u32 s22, s28, s29
	s_addc_u32 s23, s24, 0
	s_lshl_b32 s24, s15, 5
	s_and_b32 s24, s24, 0x300
	s_add_u32 s28, s41, s24
	v_lshlrev_b32_e32 v58, 4, v2
	s_waitcnt vmcnt(0)
	v_exp_f32_e64 v0, -v0
	v_lshlrev_b32_e32 v2, 2, v1
	s_addc_u32 s29, s42, 0
	v_readlane_b32 s42, v254, 50
	v_fmamk_f32 v7, v0, 0x3e2aaaab, v7
	v_fmaak_f32 v7, v0, v7, 0x3e800000
	v_fmaak_f32 v7, v0, v7, 0x3eaaaaab
	v_fma_f32 v7, v0, v7, 0.5
	v_fma_f32 v7, v0, v7, 1.0
	v_mul_f32_e32 v0, v0, v7
	v_mul_f32_e32 v0, 0xbfb8aa3b, v0
	v_mul_f32_e32 v46, v0, v3
	v_mul_f32_e32 v3, v0, v4
	v_mul_f32_e32 v4, v0, v5
	v_exp_f32_e32 v200, v4
	v_mul_f32_e32 v4, v0, v6
	v_exp_f32_e32 v201, v4
	v_xor_b32_e32 v4, 31, v176
	v_cndmask_b32_e64 v4, v176, v4, s[36:37]
	v_cvt_f32_ubyte0_e32 v4, v4
	v_mul_f32_e32 v4, v0, v4
	v_exp_f32_e32 v50, v4
	v_or_b32_e32 v4, 1, v176
	v_xor_b32_e32 v5, 30, v176
	v_cndmask_b32_e64 v4, v4, v5, s[36:37]
	v_cvt_f32_ubyte0_e32 v4, v4
	v_mul_f32_e32 v4, v0, v4
	v_exp_f32_e32 v51, v4
	v_or_b32_e32 v4, 2, v176
	v_xor_b32_e32 v5, 29, v176
	v_cndmask_b32_e64 v4, v4, v5, s[36:37]
	v_cvt_f32_ubyte0_e32 v4, v4
	v_mul_f32_e32 v4, v0, v4
	v_exp_f32_e32 v52, v4
	v_or_b32_e32 v4, 3, v176
	v_xor_b32_e32 v5, 28, v176
	v_cndmask_b32_e64 v4, v4, v5, s[36:37]
	v_cvt_f32_ubyte0_e32 v4, v4
	v_mul_f32_e32 v4, v0, v4
	v_exp_f32_e32 v53, v4
	v_or_b32_e32 v4, 4, v176
	v_xor_b32_e32 v5, 27, v176
	v_cndmask_b32_e64 v4, v4, v5, s[36:37]
	v_cvt_f32_ubyte0_e32 v4, v4
	v_mul_f32_e32 v4, v0, v4
	v_exp_f32_e32 v54, v4
	v_or_b32_e32 v4, 5, v176
	v_xor_b32_e32 v5, 26, v176
	v_cndmask_b32_e64 v4, v4, v5, s[36:37]
	v_cvt_f32_ubyte0_e32 v4, v4
	v_mul_f32_e32 v4, v0, v4
	v_exp_f32_e32 v55, v4
	v_or_b32_e32 v4, 6, v176
	v_xor_b32_e32 v5, 25, v176
	v_exp_f32_e32 v199, v3
	v_sub_u32_e32 v3, v40, v42
	v_cndmask_b32_e64 v4, v4, v5, s[36:37]
	v_cndmask_b32_e64 v3, v11, v3, s[36:37]
	v_cvt_f32_ubyte0_e32 v4, v4
	v_cvt_f32_i32_e32 v3, v3
	v_mul_f32_e32 v4, v0, v4
	v_exp_f32_e32 v56, v4
	v_or_b32_e32 v4, 7, v176
	v_xor_b32_e32 v5, 24, v176
	v_cndmask_b32_e64 v4, v4, v5, s[36:37]
	v_cvt_f32_ubyte0_e32 v4, v4
	v_mul_f32_e32 v7, 0x41800000, v0
	v_mul_f32_e32 v3, v0, v3
	v_mul_f32_e32 v0, v0, v4
	v_exp_f32_e32 v57, v0
	v_lshlrev_b32_e32 v0, 1, v1
	v_and_b32_e32 v203, 32, v0
	v_lshrrev_b32_e32 v0, 2, v1
	v_and_b32_e32 v0, 8, v0
	v_and_b32_e32 v4, 32, v2
	s_lshl_b64 s[26:27], s[26:27], 1
	v_exp_f32_e32 v202, v3
	v_bfe_u32 v3, v1, 2, 2
	v_bitop3_b32 v61, v203, v4, v0 bitop3:0x36
	v_mov_b32_e32 v0, s42
	s_movk_i32 s41, 0x90
	s_add_u32 s26, s28, s26
	v_mad_u32_u24 v63, v40, s41, v0
	v_or_b32_e32 v0, v176, v3
	v_lshlrev_b32_e32 v3, 3, v1
	s_addc_u32 s27, s29, s27
	v_ashrrev_i32_e32 v162, 5, v1
	v_bitop3_b32 v59, v58, v2, 32 bitop3:0x78
	v_lshl_or_b32 v60, s25, 4, v40
	s_movk_i32 s29, 0x240
	v_mul_u32_u24_e32 v2, 0x110, v0
	s_add_i32 s25, 0, 0x12000
	v_and_b32_e32 v3, 24, v3
	v_add3_u32 v64, s25, v2, v3
	v_mul_lo_u32 v2, v162, s29
	v_lshlrev_b32_e32 v4, 4, v1
	v_add_u32_e32 v68, 0, v2
	v_and_b32_e32 v2, 0x1c0, v4
	v_ashrrev_i32_e32 v166, 4, v1
	v_mul_u32_u24_e32 v0, 0x240, v0
	v_lshrrev_b32_e32 v1, 3, v1
	v_add3_u32 v69, v68, v2, v3
	v_or_b32_e32 v2, v3, v2
; #define LAS __attribute__((address_space(3)))
; __device__ __forceinline__ void ret_item(LAS unsigned char* lds, const bf16_t* proj, bf16_t* OD, int b, int h, int dir, int vs, float lg2) {
;     ...
;     LAS unsigned char* pVt = lds + VS + (8 * g + q4) * RSV + (16 * wid + 4 * pp) * 2;
;     LAS unsigned char* pKe = lds + KS + (8 * g + q4) * RSQ + 8 * pp + 32 * (g & 1);
;     LAS unsigned char* pKo = lds + KS + (8 * g + q4) * RSQ + 8 * pp - 32 * (g & 1);
;     const int sb3 = (qrow >> 3) & 1;
;     LAS unsigned char* wQ = lds + QS + qrow * RSQ + ((16 * qpc) ^ (32 * sb3));
;     LAS unsigned char* wK0 = lds + KS + qrow * RSQ + ((64 * (qpc >> 2) + 8 * (qpc & 3)) ^ (32 * sb3));
;     LAS unsigned char* wK1 = lds + KS + qrow * RSQ + ((64 * (qpc >> 2) + 32 + 8 * (qpc & 3)) ^ (32 * sb3));
;     {   const int c0 = dir ? 63 : 0; const size_t t0 = (size_t)c0 * CH;
; #pragma unroll
;         for (int k = 0; k < 4; ++k) { pq[k] = *(const bf16x8*)(Qg + (t0 + qrow + 16 * k) * R_IN + qpc * 8); pk[k] = *(const bf16x8*)(Kg + (t0 + qrow + 16 * k) * R_IN + qpc * 8); }
; #pragma unroll
;         for (int k = 0; k < 2; ++k) pv[k] = *(const bf16x8*)(Vg + (t0 + vrow + 32 * k) * R_IN + vpc * 8);
;     }
;     ...
;             for (int tt = 0; tt < 2; ++tt) { const f32x4 sv = tt ? sa1 : sa0; const int dt = dir ? (sjt0 + tt - sit) : (sit - sjt0 - tt);
;                 const float cs = dt <= 0 ? 1.f : dt == 1 ? c16 : dt == 2 ? c32 : c48; float w[4];
; #pragma unroll
;                 for (int r = 0; r < 4; ++r) { const bool on = dt > 0 || (dt == 0 && (dir ? (4 * g + r > l15) : (l15 >= 4 * g + r))); w[r] = on ? sv[r] * d4[r] * cs : 0.f; }
	v_lshl_add_u64 v[160:161], s[26:27], 0, v[176:177]
	v_add3_u32 v204, 0, v0, v3
	v_and_b32_e32 v0, 0x1f0, v4
	v_and_b32_e32 v66, 32, v1
	s_movk_i32 s26, 0x1f0
	v_bitop3_b32 v70, v2, v1, 32 bitop3:0x72
	s_and_b32 s28, s40, 0xfc0
	v_mov_b32_e32 v1, v177
	v_bitop3_b32 v67, v4, v66, s26 bitop3:0x6c
	v_add_u32_e32 v2, s28, v162
	v_lshl_add_u64 v[168:169], s[38:39], 0, v[0:1]
	s_mov_b64 s[26:27], 0x1000
	v_lshl_add_u64 v[170:171], v[168:169], 0, s[26:27]
	v_mad_i64_i32 v[24:25], s[26:27], v2, s3, v[168:169]
	v_add_co_u32_e64 v8, s[38:39], s65, v24
	v_mad_i64_i32 v[26:27], s[26:27], v2, s3, v[170:171]
	s_nop 0
	v_addc_co_u32_e64 v9, s[38:39], 0, v25, s[38:39]
	v_add_co_u32_e64 v12, s[38:39], s65, v26
	s_add_u32 s22, s22, s24
	s_nop 0
	v_addc_co_u32_e64 v13, s[38:39], 0, v27, s[38:39]
	v_add_co_u32_e64 v16, s[38:39], s64, v24
	v_exp_f32_e32 v47, v7
	s_nop 0
	v_addc_co_u32_e64 v17, s[38:39], 0, v25, s[38:39]
	v_add_co_u32_e64 v20, s[38:39], s64, v26
	v_lshl_or_b32 v32, s17, 4, v40
	s_nop 0
	v_addc_co_u32_e64 v21, s[38:39], 0, v27, s[38:39]
	v_mul_lo_u32 v33, v60, s29
	global_load_dwordx4 v[0:3], v[24:25], off
	global_load_dwordx4 v[4:7], v[26:27], off
	v_add_co_u32_e64 v24, s[38:39], s70, v24
	s_addc_u32 s23, s23, 0
	v_lshlrev_b32_e32 v44, 4, v40
	v_mov_b32_e32 v45, v177
	v_addc_co_u32_e64 v25, s[38:39], 0, v25, s[38:39]
	v_mad_u32_u24 v71, v32, s29, 0
	v_add_u32_e32 v72, 0, v33
	v_lshl_add_u64 v[32:33], s[22:23], 0, v[44:45]
	s_mov_b64 s[22:23], 0x2000
	v_add_co_u32_e64 v28, s[38:39], s70, v26
	v_add_u32_e32 v34, s28, v166
	v_lshl_add_u64 v[172:173], v[32:33], 0, s[22:23]
	v_addc_co_u32_e64 v29, s[38:39], 0, v27, s[38:39]
	v_mad_i64_i32 v[32:33], s[22:23], v34, s3, v[172:173]
	v_add_co_u32_e64 v36, s[38:39], s64, v32
	global_load_dwordx4 v[8:11], v[8:9], off
	s_nop 0
	global_load_dwordx4 v[12:15], v[12:13], off
	v_addc_co_u32_e64 v37, s[38:39], 0, v33, s[38:39]
	global_load_dwordx4 v[16:19], v[16:17], off
	s_nop 0
	global_load_dwordx4 v[20:23], v[20:21], off
	s_nop 0
	global_load_dwordx4 v[24:27], v[24:25], off
	s_nop 0
	global_load_dwordx4 v[28:31], v[28:29], off
	s_nop 0
	global_load_dwordx4 v[32:35], v[32:33], off
	s_nop 0
	global_load_dwordx4 v[36:39], v[36:37], off
	v_mad_u32_u24 v62, v40, s29, 0
	s_lshl_b32 s29, s20, 5
	s_cmp_eq_u32 s21, 1
	s_cselect_b64 s[38:39], -1, 0
	s_cmp_eq_u32 s21, 2
	v_readlane_b32 s44, v253, 8
	v_readlane_b32 s45, v253, 9
	v_exp_f32_e32 v45, v46
	v_mul_lo_u32 v46, v60, s41
	s_cselect_b64 s[40:41], -1, 0
	s_cmp_gt_i32 s21, 0
	v_mul_f32_e32 v48, v47, v47
	s_movk_i32 s20, 0x110
	s_cselect_b64 s[44:45], -1, 0
	s_cmp_lg_u32 s21, 0
	v_mul_f32_e32 v49, v47, v48
	v_add3_u32 v205, s42, v176, v46
	v_mul_lo_u32 v46, v166, s20
	s_cselect_b64 s[20:21], -1, 0
	s_lshl_b32 s17, s17, 5
	v_cndmask_b32_e64 v60, v49, v48, s[40:41]
	s_cmp_eq_u32 s19, 1
	v_cndmask_b32_e64 v60, v60, v47, s[38:39]
	s_cselect_b64 s[38:39], -1, 0
	s_cmp_eq_u32 s19, 2
	s_cselect_b64 s[40:41], -1, 0
	s_cmp_gt_i32 s19, 0
	s_cselect_b64 s[52:53], -1, 0
	s_cmp_lg_u32 s19, 0
	v_readlane_b32 s50, v253, 14
	v_readlane_b32 s51, v253, 15
	v_cndmask_b32_e64 v206, 1.0, v60, s[44:45]
	v_cndmask_b32_e64 v60, v49, v48, s[40:41]
	s_cselect_b64 s[22:23], -1, 0
	s_xor_b64 s[26:27], s[36:37], vcc
	v_cmp_le_u32_e32 vcc, v43, v40
	v_cndmask_b32_e64 v60, v60, v47, s[38:39]
	v_cmp_ge_u32_e64 s[38:39], v40, v41
	s_xor_b64 s[50:51], s[36:37], vcc
	v_cmp_le_u32_e32 vcc, v42, v40
	v_readlane_b32 s43, v253, 7
	v_add_u32_e32 v44, s25, v44
	s_xor_b64 s[24:25], s[36:37], s[38:39]
	s_xor_b64 s[76:77], s[36:37], vcc
	v_lshlrev_b32_e32 v224, 12, v40
	v_cndmask_b32_e64 v40, v49, 1.0, s[36:37]
	s_nor_b64 s[38:39], s[20:21], s[24:25]
	s_nor_b64 s[40:41], s[20:21], s[26:27]
	s_nor_b64 s[42:43], s[20:21], s[50:51]
	s_nor_b64 s[20:21], s[20:21], s[76:77]
	v_readlane_b32 s46, v253, 10
; __device__ __forceinline__ unsigned cvtpk(float lo, float hi) { unsigned r; asm volatile("v_cvt_pk_bf16_f32 %0, %1, %2" : "=v"(r) : "v"(lo), "v"(hi)); return r; }
; #define MF16(a, b, c) __builtin_amdgcn_mfma_f32_16x16x32_bf16((a), (b), (c), 0, 0, 0)
; __device__ __forceinline__ unsigned cvtpk(float lo, float hi) { unsigned r; asm volatile("v_cvt_pk_bf16_f32 %0, %1, %2" : "=v"(r) : "v"(lo), "v"(hi)); return r; }
; #define SCHED() __builtin_amdgcn_sched_barrier(0)
; __device__ __forceinline__ void ret_item(LAS unsigned char* lds, const bf16_t* proj, bf16_t* OD, int b, int h, int dir, int vs, float lg2) {
;     ...
;     for (int i = 0; i < 16; ++i) st[i] = (f32x4){0.f, 0.f, 0.f, 0.f};
;     const int qrow = tid >> 5, qpc = tid & 31, vrow = tid >> 4, vpc = tid & 15;
;     bf16x8 pq[4], pk[4], pv[2];
;     const float c16 = __builtin_amdgcn_exp2f(16.f * lg2), c32 = c16 * c16, c48 = c32 * c16, cd = c32 * c32;
;     const float qdl = __builtin_amdgcn_exp2f((float)(dir ? 16 - l15 : l15 + 1) * lg2);
;     float kd8[8], d4[4];
; #pragma unroll
;     for (int r = 0; r < 4; ++r) d4[r] = __builtin_amdgcn_exp2f((float)(dir ? 4 * g + r - l15 : l15 - 4 * g - r) * lg2);
; #pragma unroll
;     for (int jj = 0; jj < 8; ++jj) kd8[jj] = __builtin_amdgcn_exp2f((float)(dir ? 8 * g + jj : 31 - 8 * g - jj) * lg2);
;     ...
;         for (int it = 0; it < 4; ++it) { const int ex = dir ? 3 - it : it; const float cq = qdl * (ex == 0 ? 1.f : ex == 1 ? c16 : ex == 2 ? c32 : c48); acc[it] = acc[it] * cq; }
; #pragma unroll
;         for (int s = 0; s < 2; ++s)
; #pragma unroll
;             for (int it = 0; it < 4; ++it) acc[it] = MF16(bv[s], ia[s][it], acc[it]);
;         SCHED();
; #pragma unroll
;         for (int i = 0; i < 16; ++i) st[i] = st[i] * cd;
;         bf16x8 bvd[2];
; #pragma unroll
;         for (int s = 0; s < 2; ++s) { const float ck = (dir ? s : 1 - s) ? c32 : 1.f; float e[8];
; #pragma unroll
;             for (int jj = 0; jj < 8; ++jj) e[jj] = bf2f((unsigned short)bv[s][jj]) * (kd8[jj] * ck);
;             u32x4 bw; bw.x = cvtpk(e[0], e[1]); bw.y = cvtpk(e[2], e[3]); bw.z = cvtpk(e[4], e[5]); bw.w = cvtpk(e[6], e[7]);
;             bvd[s] = __builtin_bit_cast(bf16x8, bw); }
	v_readlane_b32 s47, v253, 11
	v_mul_f32_e32 v178, v45, v40
	v_cndmask_b32_e64 v40, v48, v47, s[36:37]
	s_or_b64 s[38:39], s[44:45], s[38:39]
	s_or_b64 s[40:41], s[44:45], s[40:41]
	s_or_b64 s[42:43], s[44:45], s[42:43]
	s_or_b64 s[44:45], s[44:45], s[20:21]
	s_nor_b64 s[20:21], s[22:23], s[24:25]
	v_mul_f32_e32 v182, v45, v40
	v_cndmask_b32_e64 v40, v47, v48, s[36:37]
	s_or_b64 s[46:47], s[52:53], s[20:21]
	s_nor_b64 s[20:21], s[22:23], s[26:27]
	v_cndmask_b32_e64 v207, 1.0, v60, s[52:53]
	v_cndmask_b32_e64 v60, 1.0, v48, s[36:37]
	v_mul_f32_e32 v186, v45, v40
	v_cndmask_b32_e64 v40, 1.0, v49, s[36:37]
	s_or_b64 s[48:49], s[52:53], s[20:21]
	s_nor_b64 s[20:21], s[22:23], s[50:51]
	v_mul_f32_e32 v164, v48, v48
	v_sub_u32_e32 v65, 0, v203
	v_mul_f32_e32 v208, v50, v60
	v_mul_f32_e32 v209, v51, v60
	v_mul_f32_e32 v210, v52, v60
	v_mul_f32_e32 v211, v53, v60
	v_mul_f32_e32 v212, v54, v60
	v_mul_f32_e32 v213, v55, v60
	v_mul_f32_e32 v214, v56, v60
	v_mul_f32_e32 v215, v57, v60
	v_cndmask_b32_e64 v60, v48, 1.0, s[36:37]
	v_mul_f32_e32 v190, v45, v40
	s_or_b64 s[50:51], s[52:53], s[20:21]
	s_nor_b64 s[20:21], s[22:23], s[76:77]
	v_mov_b32_e32 v40, 0
	s_mov_b32 s16, 1
	v_ashrrev_i32_e32 v163, 31, v162
	v_ashrrev_i32_e32 v167, 31, v166
	v_mov_b32_e32 v174, v164
	v_mov_b32_e32 v175, v164
	s_lshl_b32 s18, s18, 5
	v_mul_f32_e32 v216, v50, v60
	v_mul_f32_e32 v217, v51, v60
	v_mul_f32_e32 v218, v52, v60
	v_mul_f32_e32 v219, v53, v60
	v_mul_f32_e32 v220, v54, v60
	v_mul_f32_e32 v221, v55, v60
	v_mul_f32_e32 v222, v56, v60
	v_mul_f32_e32 v223, v57, v60
	v_mov_b32_e32 v179, v178
	v_mov_b32_e32 v180, v178
	v_mov_b32_e32 v181, v178
	v_mov_b32_e32 v183, v182
	v_mov_b32_e32 v184, v182
	v_mov_b32_e32 v185, v182
	v_mov_b32_e32 v187, v186
	v_mov_b32_e32 v188, v186
	v_mov_b32_e32 v189, v186
	v_mov_b32_e32 v191, v190
	v_mov_b32_e32 v192, v190
	v_mov_b32_e32 v193, v190
	s_or_b64 s[52:53], s[52:53], s[20:21]
	s_mov_b32 s19, 62
	v_add_u32_e32 v225, v68, v67
	v_add_u32_e32 v226, v69, v66
	v_add_u32_e32 v227, v68, v70
	v_add_u32_e32 v228, v44, v46
	v_add_u32_e32 v229, v72, v61
	v_add_u32_e32 v230, v71, v59
	v_add_u32_e32 v231, v62, v59
	v_add_u32_e32 v232, s29, v64
	v_add_u32_e32 v233, v63, v58
	v_add_u32_e32 v234, v204, v65
	v_mov_b32_e32 v41, v40
	v_mov_b32_e32 v42, v40
	v_mov_b32_e32 v43, v40
	v_mov_b32_e32 v52, v40
	v_mov_b32_e32 v53, v40
	v_mov_b32_e32 v54, v40
	v_mov_b32_e32 v55, v40
	v_mov_b32_e32 v48, v40
	v_mov_b32_e32 v49, v40
	v_mov_b32_e32 v50, v40
	v_mov_b32_e32 v51, v40
	v_mov_b32_e32 v44, v40
	v_mov_b32_e32 v45, v40
	v_mov_b32_e32 v46, v40
	v_mov_b32_e32 v47, v40
	v_mov_b32_e32 v68, v40
	v_mov_b32_e32 v69, v40
	v_mov_b32_e32 v70, v40
	v_mov_b32_e32 v71, v40
	v_mov_b32_e32 v64, v40
	v_mov_b32_e32 v65, v40
	v_mov_b32_e32 v66, v40
	v_mov_b32_e32 v67, v40
	v_mov_b32_e32 v60, v40
	v_mov_b32_e32 v61, v40
	v_mov_b32_e32 v62, v40
	v_mov_b32_e32 v63, v40
	v_mov_b32_e32 v56, v40
	v_mov_b32_e32 v57, v40
	v_mov_b32_e32 v58, v40
	v_mov_b32_e32 v59, v40
	v_mov_b32_e32 v88, v40
	v_mov_b32_e32 v89, v40
	v_mov_b32_e32 v90, v40
	v_mov_b32_e32 v91, v40
	v_mov_b32_e32 v80, v40
	v_mov_b32_e32 v81, v40
	v_mov_b32_e32 v82, v40
	v_mov_b32_e32 v83, v40
	v_mov_b32_e32 v76, v40
	v_mov_b32_e32 v77, v40
	v_mov_b32_e32 v78, v40
	v_mov_b32_e32 v79, v40
	v_mov_b32_e32 v72, v40
	v_mov_b32_e32 v73, v40
	v_mov_b32_e32 v74, v40
	v_mov_b32_e32 v75, v40
	v_mov_b32_e32 v92, v40
	v_mov_b32_e32 v93, v40
	v_mov_b32_e32 v94, v40
	v_mov_b32_e32 v95, v40
	v_mov_b32_e32 v84, v40
	v_mov_b32_e32 v85, v40
	v_mov_b32_e32 v86, v40
	v_mov_b32_e32 v87, v40
	v_mov_b32_e32 v96, v40
	v_mov_b32_e32 v97, v40
	v_mov_b32_e32 v98, v40
	v_mov_b32_e32 v99, v40
	v_mov_b32_e32 v100, v40
	v_mov_b32_e32 v101, v40
	v_mov_b32_e32 v102, v40
	v_mov_b32_e32 v103, v40
	s_waitcnt vmcnt(0)
	s_branch .LBB0_141

; #define LAS __attribute__((address_space(3)))
; __device__ __forceinline__ void ret_item(LAS unsigned char* lds, const bf16_t* proj, bf16_t* OD, int b, int h, int dir, int vs, float lg2) {
;     ...
;         const int c = dir ? 63 - step : step; const size_t t0 = (size_t)c * CH;
; #pragma unroll
;         for (int k = 0; k < 4; ++k) { *(LAS bf16x8*)(wQ + 16 * k * RSQ) = pq[k];
;             *(LAS s16x4*)(wK0 + 16 * k * RSQ) = (s16x4){pk[k][0], pk[k][1], pk[k][2], pk[k][3]}; *(LAS s16x4*)(wK1 + 16 * k * RSQ) = (s16x4){pk[k][4], pk[k][5], pk[k][6], pk[k][7]}; }
; #pragma unroll
;         for (int k = 0; k < 2; ++k) *(LAS bf16x8*)(lds + VS + (vrow + 32 * k) * RSV + vpc * 16) = pv[k];
;         if (step + 1 < 64) { const int c1 = dir ? 62 - step : step + 1; const size_t t1 = (size_t)c1 * CH;
; #pragma unroll
;             for (int k = 0; k < 4; ++k) { pq[k] = *(const bf16x8*)(Qg + (t1 + qrow + 16 * k) * R_IN + qpc * 8); pk[k] = *(const bf16x8*)(Kg + (t1 + qrow + 16 * k) * R_IN + qpc * 8); }
; #pragma unroll
;             for (int k = 0; k < 2; ++k) pv[k] = *(const bf16x8*)(Vg + (t1 + vrow + 32 * k) * R_IN + vpc * 8);
;         }
.LBB0_141:
	v_add_co_u32_e64 v104, s[20:21], s19, 1
	s_and_b64 vcc, exec, s[20:21]
	s_waitcnt vmcnt(13)
	ds_write_b128 v225, v[0:3]
	s_waitcnt vmcnt(12)
	ds_write_b64 v226, v[4:5] offset:36864
	s_waitcnt vmcnt(11)
	ds_write_b128 v225, v[8:11] offset:9216
	s_waitcnt vmcnt(10)
	ds_write_b64 v226, v[12:13] offset:46080
	ds_write2st64_b64 v227, v[6:7], v[14:15] offset0:72 offset1:90
	s_waitcnt vmcnt(9)
	ds_write_b128 v225, v[16:19] offset:18432
	s_waitcnt vmcnt(8)
	ds_write_b64 v226, v[20:21] offset:55296
	s_waitcnt vmcnt(7)
	ds_write_b128 v225, v[24:27] offset:27648
	s_waitcnt vmcnt(6)
	ds_write_b64 v226, v[28:29] offset:64512
	ds_write2st64_b64 v227, v[22:23], v[30:31] offset0:108 offset1:126
	s_waitcnt vmcnt(5)
	ds_write_b128 v228, v[32:35]
	s_waitcnt vmcnt(4)
	ds_write_b128 v228, v[36:39] offset:8704
	s_cbranch_vccnz .LBB0_140
	s_and_b64 s[20:21], s[36:37], exec
	s_cselect_b32 s20, s16, s19
	s_ashr_i32 s21, s20, 31
	s_lshl_b64 s[20:21], s[20:21], 6
	v_lshl_add_u64 v[0:1], s[20:21], 0, v[162:163]
	v_mad_u64_u32 v[24:25], s[22:23], v0, s3, v[168:169]
	v_mad_i32_i24 v25, v1, s3, v25
	v_add_co_u32_e32 v8, vcc, s65, v24
	v_mad_u64_u32 v[26:27], s[22:23], v0, s3, v[170:171]
	s_nop 0
	v_addc_co_u32_e32 v9, vcc, 0, v25, vcc
	v_mad_i32_i24 v27, v1, s3, v27
	v_add_co_u32_e32 v12, vcc, s65, v26
	global_load_dwordx4 v[0:3], v[24:25], off
	global_load_dwordx4 v[4:7], v[26:27], off
	v_addc_co_u32_e32 v13, vcc, 0, v27, vcc
	v_add_co_u32_e32 v16, vcc, s64, v24
	v_lshl_add_u64 v[32:33], s[20:21], 0, v[166:167]
	s_nop 0
	v_addc_co_u32_e32 v17, vcc, 0, v25, vcc
	v_add_co_u32_e32 v20, vcc, s64, v26
	v_mad_u64_u32 v[34:35], s[20:21], v32, s3, v[172:173]
	s_nop 0
	v_addc_co_u32_e32 v21, vcc, 0, v27, vcc
	v_add_co_u32_e32 v24, vcc, s70, v24
	v_mad_i32_i24 v35, v33, s3, v35
	s_nop 0
	v_addc_co_u32_e32 v25, vcc, 0, v25, vcc
	v_add_co_u32_e32 v28, vcc, 0x120000, v26
	global_load_dwordx4 v[8:11], v[8:9], off
	s_nop 0
	global_load_dwordx4 v[12:15], v[12:13], off
	v_addc_co_u32_e32 v29, vcc, 0, v27, vcc
	v_add_co_u32_e32 v36, vcc, 0xc0000, v34
	global_load_dwordx4 v[16:19], v[16:17], off
	s_nop 0
	global_load_dwordx4 v[20:23], v[20:21], off
	v_addc_co_u32_e32 v37, vcc, 0, v35, vcc
	global_load_dwordx4 v[24:27], v[24:25], off
	s_nop 0
	global_load_dwordx4 v[28:31], v[28:29], off
	s_nop 0
	global_load_dwordx4 v[32:35], v[34:35], off
	s_nop 0
	global_load_dwordx4 v[36:39], v[36:37], off
	s_branch .LBB0_140

;     __device__ __forceinline__ void operator()(f32x4 (&acc)[2][2][4][2], const Unit& u, int wr, int wc, int fr, int fq, LAS unsigned char* lds) const {
;     ...
;         if (tid < 256) { const unsigned long long* slot = (const unsigned long long*)xch + (size_t)(u.pm * BM + tid) * 8; float sv = 0.f, qv = 0.f;
; #pragma unroll
;             for (int t = 0; t < 8; ++t) { const unsigned long long w = __hip_atomic_load(slot + t, __ATOMIC_RELAXED, __HIP_MEMORY_SCOPE_AGENT); sv += __uint_as_float((unsigned)w); qv += __uint_as_float((unsigned)(w >> 32)); }
;             const float mean = sv * (1.f / DM); const float var = fmaxf(qv * (1.f / DM) - mean * mean, 0.f);
;             ST[tid] = (f32x2){mean, __builtin_amdgcn_rsqf(var + LN_EPS)}; }
.LBB0_397:
	s_waitcnt vmcnt(0) lgkmcnt(0)
	s_barrier
	s_lshl_b32 s21, s21, 8
	s_and_saveexec_b64 s[78:79], s[40:41]
	s_cbranch_execz .LBB0_399
	v_add_u32_e32 v146, s21, v150
	v_ashrrev_i32_e32 v147, 31, v146
	v_lshlrev_b64 v[146:147], 6, v[146:147]
	v_lshl_add_u64 v[146:147], s[28:29], 0, v[146:147]
	s_waitcnt lgkmcnt(0)
	global_load_dwordx2 v[182:183], v[146:147], off sc1
	global_load_dwordx2 v[184:185], v[146:147], off offset:8 sc1
	global_load_dwordx2 v[186:187], v[146:147], off offset:16 sc1
	global_load_dwordx2 v[188:189], v[146:147], off offset:24 sc1
	global_load_dwordx2 v[190:191], v[146:147], off offset:32 sc1
	global_load_dwordx2 v[192:193], v[146:147], off offset:40 sc1
	global_load_dwordx2 v[194:195], v[146:147], off offset:48 sc1
	global_load_dwordx2 v[196:197], v[146:147], off offset:56 sc1
	s_mov_b32 s22, 0x3a000000
	s_waitcnt vmcnt(7)
	v_add_f32_e32 v151, 0, v182
	v_add_f32_e32 v172, 0, v183
	s_waitcnt vmcnt(6)
	v_add_f32_e32 v151, v151, v184
	v_add_f32_e32 v172, v172, v185
	s_waitcnt vmcnt(5)
	v_add_f32_e32 v151, v151, v186
	v_add_f32_e32 v172, v172, v187
	s_waitcnt vmcnt(4)
	v_add_f32_e32 v151, v151, v188
	v_add_f32_e32 v172, v172, v189
	s_waitcnt vmcnt(3)
	v_add_f32_e32 v151, v151, v190
	v_add_f32_e32 v172, v172, v191
	s_waitcnt vmcnt(2)
	v_add_f32_e32 v151, v151, v192
	v_add_f32_e32 v172, v172, v193
	s_waitcnt vmcnt(1)
	v_add_f32_e32 v148, v151, v194
	v_add_f32_e32 v149, v172, v195
	s_waitcnt vmcnt(0)
	v_add_f32_e32 v146, v148, v196
	v_mul_f32_e32 v146, 0x3a000000, v146
	v_add_f32_e32 v147, v149, v197
	v_mul_f32_e32 v148, v146, v146
	v_fma_f32 v147, v147, s22, -v148
	v_max_f32_e32 v147, 0, v147
	v_add_f32_e32 v147, 0x3727c5ac, v147
	v_rsq_f32_e32 v147, v147
	v_lshl_add_u32 v148, v150, 3, 0
	v_add_u32_e32 v148, 0x22400, v148
	ds_write_b64 v148, v[146:147]

;     __device__ __forceinline__ void operator()(f32x4 (&acc)[2][2][4][2], const Unit& u, int wr, int wc, int fr, int fq, LAS unsigned char* lds) const {
;     ...
;         if (tid < 256) { const unsigned long long* slot = (const unsigned long long*)xch + (size_t)(u.pm * BM + tid) * 8; float sv = 0.f, qv = 0.f;
; #pragma unroll
;             for (int t = 0; t < 8; ++t) { const unsigned long long w = __hip_atomic_load(slot + t, __ATOMIC_RELAXED, __HIP_MEMORY_SCOPE_AGENT); sv += __uint_as_float((unsigned)w); qv += __uint_as_float((unsigned)(w >> 32)); }
;             const float mean = sv * (1.f / DM); const float var = fmaxf(qv * (1.f / DM) - mean * mean, 0.f);
;             ST[tid] = (f32x2){mean, __builtin_amdgcn_rsqf(var + LN_EPS)}; }
.LBB0_505:
	s_waitcnt vmcnt(0) lgkmcnt(0)
	s_barrier
	s_lshl_b32 s18, s18, 8
	s_and_saveexec_b64 s[74:75], s[38:39]
	s_cbranch_execz .LBB0_507
	v_add_u32_e32 v156, s18, v160
	v_ashrrev_i32_e32 v157, 31, v156
	v_lshlrev_b64 v[156:157], 6, v[156:157]
	v_lshl_add_u64 v[156:157], s[26:27], 0, v[156:157]
	s_waitcnt lgkmcnt(0)
	global_load_dwordx2 v[188:189], v[156:157], off sc1
	global_load_dwordx2 v[190:191], v[156:157], off offset:8 sc1
	global_load_dwordx2 v[192:193], v[156:157], off offset:16 sc1
	global_load_dwordx2 v[194:195], v[156:157], off offset:24 sc1
	global_load_dwordx2 v[196:197], v[156:157], off offset:32 sc1
	global_load_dwordx2 v[200:201], v[156:157], off offset:40 sc1
	global_load_dwordx2 v[202:203], v[156:157], off offset:48 sc1
	global_load_dwordx2 v[204:205], v[156:157], off offset:56 sc1
	s_mov_b32 s19, 0x3a000000
	s_waitcnt vmcnt(7)
	v_add_f32_e32 v161, 0, v188
	v_add_f32_e32 v181, 0, v189
	s_waitcnt vmcnt(6)
	v_add_f32_e32 v161, v161, v190
	v_add_f32_e32 v181, v181, v191
	s_waitcnt vmcnt(5)
	v_add_f32_e32 v161, v161, v192
	v_add_f32_e32 v181, v181, v193
	s_waitcnt vmcnt(4)
	v_add_f32_e32 v161, v161, v194
	v_add_f32_e32 v181, v181, v195
	s_waitcnt vmcnt(3)
	v_add_f32_e32 v161, v161, v196
	v_add_f32_e32 v181, v181, v197
	s_waitcnt vmcnt(2)
	v_add_f32_e32 v161, v161, v200
	v_add_f32_e32 v181, v181, v201
	s_waitcnt vmcnt(1)
	v_add_f32_e32 v158, v161, v202
	v_add_f32_e32 v159, v181, v203
	s_waitcnt vmcnt(0)
	v_add_f32_e32 v156, v158, v204
	v_mul_f32_e32 v156, 0x3a000000, v156
	v_add_f32_e32 v157, v159, v205
	v_mul_f32_e32 v158, v156, v156
	v_fma_f32 v157, v157, s19, -v158
	v_max_f32_e32 v157, 0, v157
	v_add_f32_e32 v157, 0x3727c5ac, v157
	v_rsq_f32_e32 v157, v157
	v_lshl_add_u32 v158, v160, 3, 0
	v_add_u32_e32 v158, 0x22400, v158
	ds_write_b64 v158, v[156:157]
